# attention unit epilogue: first-component O scratch written and re-read with coalesced dwordx4 (32 per wave instead of 128 dword accesses)
# speedup vs baseline: 1.0092x; 1.0025x over previous
.LBB0_521:
	s_and_saveexec_b64 s[4:5], s[0:1]
	ds_write_b32 v226, v144
	s_or_b64 exec, exec, s[4:5]
	s_waitcnt lgkmcnt(0)
	v_add_u32_e32 v136, s21, v210
	ds_read_b128 v[128:131], v136
	ds_read_b128 v[132:135], v136 offset:32
	s_ashr_i32 s21, s20, 31
	s_lshl_b64 s[0:1], s[20:21], 12
	ds_read_b128 v[138:141], v136 offset:96
	s_waitcnt lgkmcnt(2)
	v_rcp_f32_e32 v142, v128
	v_rcp_f32_e32 v145, v129
	v_rcp_f32_e32 v152, v130
	v_rcp_f32_e32 v161, v131
	ds_read_b128 v[128:131], v136 offset:64
	s_waitcnt lgkmcnt(2)
	v_rcp_f32_e32 v162, v132
	v_rcp_f32_e32 v163, v133
	v_rcp_f32_e32 v164, v134
	v_rcp_f32_e32 v165, v135
	s_waitcnt lgkmcnt(0)
	v_rcp_f32_e32 v137, v128
	v_rcp_f32_e32 v136, v129
	v_rcp_f32_e32 v135, v130
	v_rcp_f32_e32 v134, v131
	v_rcp_f32_e32 v133, v138
	v_rcp_f32_e32 v132, v139
	v_rcp_f32_e32 v131, v140
	v_rcp_f32_e32 v130, v141
	s_add_u32 s0, s62, s0
	s_addc_u32 s1, s63, s1
	s_mov_b64 s[4:5], -1
	s_andn2_b64 vcc, exec, s[18:19]
	v_lshlrev_b32_e32 v210, 2, v219
	v_lshlrev_b32_e32 v128, 14, v218
	v_lshl_add_u32 v129, v218, 5, v219
	v_lshlrev_b32_e32 v128, 4, v129
	s_mov_b32 s96, s0
	s_mov_b32 s97, s1
	s_cbranch_vccnz .Lepi0_p0
	s_lshl_b64 s[4:5], s[20:21], 11
	s_add_u32 s4, s64, s4
	s_addc_u32 s5, s65, s5
	v_lshlrev_b32_e32 v140, 1, v219
	v_lshl_add_u32 v140, v218, 13, v140
	v_mov_b32_e32 v141, 0
	v_lshl_add_u64 v[146:147], s[4:5], 0, v[140:141]
	s_mov_b64 s[100:101], 0x1000
	s_mov_b64 s[98:99], 0x4000
	global_load_dwordx4 v[166:169], v128, s[96:97]
	s_add_u32 s96, s96, 0x1000
	s_addc_u32 s97, s97, 0
	global_load_dwordx4 v[170:173], v128, s[96:97]
	s_add_u32 s96, s96, 0x1000
	s_addc_u32 s97, s97, 0
	global_load_dwordx4 v[174:177], v128, s[96:97]
	s_add_u32 s96, s96, 0x1000
	s_addc_u32 s97, s97, 0
	global_load_dwordx4 v[178:181], v128, s[96:97]
	s_add_u32 s96, s96, 0x1000
	s_addc_u32 s97, s97, 0
	global_load_dwordx4 v[182:185], v128, s[96:97]
	s_add_u32 s96, s96, 0x1000
	s_addc_u32 s97, s97, 0
	global_load_dwordx4 v[186:189], v128, s[96:97]
	s_add_u32 s96, s96, 0x1000
	s_addc_u32 s97, s97, 0
	global_load_dwordx4 v[190:193], v128, s[96:97]
	s_add_u32 s96, s96, 0x1000
	s_addc_u32 s97, s97, 0
	global_load_dwordx4 v[194:197], v128, s[96:97]
	s_add_u32 s96, s96, 0x1000
	s_addc_u32 s97, s97, 0
	global_load_dwordx4 v[198:201], v128, s[96:97]
	s_add_u32 s96, s96, 0x1000
	s_addc_u32 s97, s97, 0
	global_load_dwordx4 v[202:205], v128, s[96:97]
	s_add_u32 s96, s96, 0x1000
	s_addc_u32 s97, s97, 0
	global_load_dwordx4 v[240:243], v128, s[96:97]
	s_add_u32 s96, s96, 0x1000
	s_addc_u32 s97, s97, 0
	global_load_dwordx4 v[244:247], v128, s[96:97]
	s_add_u32 s96, s96, 0x1000
	s_addc_u32 s97, s97, 0
	global_load_dwordx4 v[248:251], v128, s[96:97]
	s_add_u32 s96, s96, 0x1000
	s_addc_u32 s97, s97, 0
	global_load_dwordx4 v[252:255], v128, s[96:97]
	s_add_u32 s96, s96, 0x1000
	s_addc_u32 s97, s97, 0
	global_load_dwordx4 v[232:235], v128, s[96:97]
	s_add_u32 s96, s96, 0x1000
	s_addc_u32 s97, s97, 0
	global_load_dwordx4 v[154:157], v128, s[96:97]
	s_add_u32 s96, s96, 0x1000
	s_addc_u32 s97, s97, 0
	s_waitcnt vmcnt(8)
	v_lshl_add_u64 v[148:149], v[146:147], 0, s[100:101]
	v_mul_f32_e32 v158, v0, v142
	v_fma_f32 v166, -v209, v158, v166
	v_bfe_u32 v158, v166, 16, 1
	v_add3_u32 v166, v166, v158, s39
	global_store_short_d16_hi v[146:147], v166, off
	v_mul_f32_e32 v159, v1, v145
	v_fma_f32 v167, -v209, v159, v167
	v_bfe_u32 v159, v167, 16, 1
	v_add3_u32 v167, v167, v159, s39
	global_store_short_d16_hi v[146:147], v167, off offset:2048
	v_mul_f32_e32 v160, v2, v152
	v_fma_f32 v168, -v209, v160, v168
	v_bfe_u32 v160, v168, 16, 1
	v_add3_u32 v168, v168, v160, s39
	global_store_short_d16_hi v[148:149], v168, off
	v_mul_f32_e32 v150, v3, v161
	v_fma_f32 v169, -v209, v150, v169
	v_bfe_u32 v150, v169, 16, 1
	v_add3_u32 v169, v169, v150, s39
	global_store_short_d16_hi v[148:149], v169, off offset:2048
	v_mul_f32_e32 v158, v112, v142
	v_fma_f32 v170, -v209, v158, v170
	v_bfe_u32 v158, v170, 16, 1
	v_add3_u32 v170, v170, v158, s39
	global_store_short_d16_hi v[146:147], v170, off offset:64
	v_mul_f32_e32 v159, v113, v145
	v_fma_f32 v171, -v209, v159, v171
	v_bfe_u32 v159, v171, 16, 1
	v_add3_u32 v171, v171, v159, s39
	global_store_short_d16_hi v[146:147], v171, off offset:2112
	v_mul_f32_e32 v160, v114, v152
	v_fma_f32 v172, -v209, v160, v172
	v_bfe_u32 v160, v172, 16, 1
	v_add3_u32 v172, v172, v160, s39
	global_store_short_d16_hi v[148:149], v172, off offset:64
	v_mul_f32_e32 v150, v115, v161
	v_fma_f32 v173, -v209, v150, v173
	v_bfe_u32 v150, v173, 16, 1
	v_add3_u32 v173, v173, v150, s39
	global_store_short_d16_hi v[148:149], v173, off offset:2112
	v_mul_f32_e32 v158, v96, v142
	v_fma_f32 v174, -v209, v158, v174
	v_bfe_u32 v158, v174, 16, 1
	v_add3_u32 v174, v174, v158, s39
	global_store_short_d16_hi v[146:147], v174, off offset:128
	v_mul_f32_e32 v159, v97, v145
	v_fma_f32 v175, -v209, v159, v175
	v_bfe_u32 v159, v175, 16, 1
	v_add3_u32 v175, v175, v159, s39
	global_store_short_d16_hi v[146:147], v175, off offset:2176
	v_mul_f32_e32 v160, v98, v152
	v_fma_f32 v176, -v209, v160, v176
	v_bfe_u32 v160, v176, 16, 1
	v_add3_u32 v176, v176, v160, s39
	global_store_short_d16_hi v[148:149], v176, off offset:128
	v_mul_f32_e32 v150, v99, v161
	v_fma_f32 v177, -v209, v150, v177
	v_bfe_u32 v150, v177, 16, 1
	v_add3_u32 v177, v177, v150, s39
	global_store_short_d16_hi v[148:149], v177, off offset:2176
	v_mul_f32_e32 v158, v80, v142
	v_fma_f32 v178, -v209, v158, v178
	v_bfe_u32 v158, v178, 16, 1
	v_add3_u32 v178, v178, v158, s39
	global_store_short_d16_hi v[146:147], v178, off offset:192
	v_mul_f32_e32 v159, v81, v145
	v_fma_f32 v179, -v209, v159, v179
	v_bfe_u32 v159, v179, 16, 1
	v_add3_u32 v179, v179, v159, s39
	global_store_short_d16_hi v[146:147], v179, off offset:2240
	v_mul_f32_e32 v160, v82, v152
	v_fma_f32 v180, -v209, v160, v180
	v_bfe_u32 v160, v180, 16, 1
	v_add3_u32 v180, v180, v160, s39
	global_store_short_d16_hi v[148:149], v180, off offset:192
	v_mul_f32_e32 v150, v83, v161
	v_fma_f32 v181, -v209, v150, v181
	v_bfe_u32 v150, v181, 16, 1
	v_add3_u32 v181, v181, v150, s39
	global_store_short_d16_hi v[148:149], v181, off offset:2240
	v_mul_f32_e32 v158, v64, v142
	v_fma_f32 v182, -v209, v158, v182
	v_bfe_u32 v158, v182, 16, 1
	v_add3_u32 v182, v182, v158, s39
	global_store_short_d16_hi v[146:147], v182, off offset:256
	v_mul_f32_e32 v159, v65, v145
	v_fma_f32 v183, -v209, v159, v183
	v_bfe_u32 v159, v183, 16, 1
	v_add3_u32 v183, v183, v159, s39
	global_store_short_d16_hi v[146:147], v183, off offset:2304
	v_mul_f32_e32 v160, v66, v152
	v_fma_f32 v184, -v209, v160, v184
	v_bfe_u32 v160, v184, 16, 1
	v_add3_u32 v184, v184, v160, s39
	global_store_short_d16_hi v[148:149], v184, off offset:256
	v_mul_f32_e32 v150, v67, v161
	v_fma_f32 v185, -v209, v150, v185
	v_bfe_u32 v150, v185, 16, 1
	v_add3_u32 v185, v185, v150, s39
	global_store_short_d16_hi v[148:149], v185, off offset:2304
	v_mul_f32_e32 v158, v48, v142
	v_fma_f32 v186, -v209, v158, v186
	v_bfe_u32 v158, v186, 16, 1
	v_add3_u32 v186, v186, v158, s39
	global_store_short_d16_hi v[146:147], v186, off offset:320
	v_mul_f32_e32 v159, v49, v145
	v_fma_f32 v187, -v209, v159, v187
	v_bfe_u32 v159, v187, 16, 1
	v_add3_u32 v187, v187, v159, s39
	global_store_short_d16_hi v[146:147], v187, off offset:2368
	v_mul_f32_e32 v160, v50, v152
	v_fma_f32 v188, -v209, v160, v188
	v_bfe_u32 v160, v188, 16, 1
	v_add3_u32 v188, v188, v160, s39
	global_store_short_d16_hi v[148:149], v188, off offset:320
	v_mul_f32_e32 v150, v51, v161
	v_fma_f32 v189, -v209, v150, v189
	v_bfe_u32 v150, v189, 16, 1
	v_add3_u32 v189, v189, v150, s39
	global_store_short_d16_hi v[148:149], v189, off offset:2368
	v_mul_f32_e32 v158, v32, v142
	v_fma_f32 v190, -v209, v158, v190
	v_bfe_u32 v158, v190, 16, 1
	v_add3_u32 v190, v190, v158, s39
	global_store_short_d16_hi v[146:147], v190, off offset:384
	v_mul_f32_e32 v159, v33, v145
	v_fma_f32 v191, -v209, v159, v191
	v_bfe_u32 v159, v191, 16, 1
	v_add3_u32 v191, v191, v159, s39
	global_store_short_d16_hi v[146:147], v191, off offset:2432
	v_mul_f32_e32 v160, v34, v152
	v_fma_f32 v192, -v209, v160, v192
	v_bfe_u32 v160, v192, 16, 1
	v_add3_u32 v192, v192, v160, s39
	global_store_short_d16_hi v[148:149], v192, off offset:384
	v_mul_f32_e32 v150, v35, v161
	v_fma_f32 v193, -v209, v150, v193
	v_bfe_u32 v150, v193, 16, 1
	v_add3_u32 v193, v193, v150, s39
	global_store_short_d16_hi v[148:149], v193, off offset:2432
	v_mul_f32_e32 v158, v16, v142
	v_fma_f32 v194, -v209, v158, v194
	v_bfe_u32 v158, v194, 16, 1
	v_add3_u32 v194, v194, v158, s39
	global_store_short_d16_hi v[146:147], v194, off offset:448
	v_mul_f32_e32 v159, v17, v145
	v_fma_f32 v195, -v209, v159, v195
	v_bfe_u32 v159, v195, 16, 1
	v_add3_u32 v195, v195, v159, s39
	global_store_short_d16_hi v[146:147], v195, off offset:2496
	v_mul_f32_e32 v160, v18, v152
	v_fma_f32 v196, -v209, v160, v196
	v_bfe_u32 v160, v196, 16, 1
	v_add3_u32 v196, v196, v160, s39
	global_store_short_d16_hi v[148:149], v196, off offset:448
	v_mul_f32_e32 v150, v19, v161
	v_fma_f32 v197, -v209, v150, v197
	v_bfe_u32 v150, v197, 16, 1
	v_add3_u32 v197, v197, v150, s39
	global_store_short_d16_hi v[148:149], v197, off offset:2496
	global_load_dwordx4 v[166:169], v128, s[96:97]
	s_add_u32 s96, s96, 0x1000
	s_addc_u32 s97, s97, 0
	global_load_dwordx4 v[170:173], v128, s[96:97]
	s_add_u32 s96, s96, 0x1000
	s_addc_u32 s97, s97, 0
	global_load_dwordx4 v[174:177], v128, s[96:97]
	s_add_u32 s96, s96, 0x1000
	s_addc_u32 s97, s97, 0
	global_load_dwordx4 v[178:181], v128, s[96:97]
	s_add_u32 s96, s96, 0x1000
	s_addc_u32 s97, s97, 0
	global_load_dwordx4 v[182:185], v128, s[96:97]
	s_add_u32 s96, s96, 0x1000
	s_addc_u32 s97, s97, 0
	global_load_dwordx4 v[186:189], v128, s[96:97]
	s_add_u32 s96, s96, 0x1000
	s_addc_u32 s97, s97, 0
	global_load_dwordx4 v[190:193], v128, s[96:97]
	s_add_u32 s96, s96, 0x1000
	s_addc_u32 s97, s97, 0
	global_load_dwordx4 v[194:197], v128, s[96:97]
	s_add_u32 s96, s96, 0x1000
	s_addc_u32 s97, s97, 0
	v_lshl_add_u64 v[146:147], v[146:147], 0, s[98:99]
	s_waitcnt vmcnt(40)
	v_lshl_add_u64 v[148:149], v[146:147], 0, s[100:101]
	v_mul_f32_e32 v158, v4, v162
	v_fma_f32 v198, -v209, v158, v198
	v_bfe_u32 v158, v198, 16, 1
	v_add3_u32 v198, v198, v158, s39
	global_store_short_d16_hi v[146:147], v198, off
	v_mul_f32_e32 v159, v5, v163
	v_fma_f32 v199, -v209, v159, v199
	v_bfe_u32 v159, v199, 16, 1
	v_add3_u32 v199, v199, v159, s39
	global_store_short_d16_hi v[146:147], v199, off offset:2048
	v_mul_f32_e32 v160, v6, v164
	v_fma_f32 v200, -v209, v160, v200
	v_bfe_u32 v160, v200, 16, 1
	v_add3_u32 v200, v200, v160, s39
	global_store_short_d16_hi v[148:149], v200, off
	v_mul_f32_e32 v150, v7, v165
	v_fma_f32 v201, -v209, v150, v201
	v_bfe_u32 v150, v201, 16, 1
	v_add3_u32 v201, v201, v150, s39
	global_store_short_d16_hi v[148:149], v201, off offset:2048
	v_mul_f32_e32 v158, v116, v162
	v_fma_f32 v202, -v209, v158, v202
	v_bfe_u32 v158, v202, 16, 1
	v_add3_u32 v202, v202, v158, s39
	global_store_short_d16_hi v[146:147], v202, off offset:64
	v_mul_f32_e32 v159, v117, v163
	v_fma_f32 v203, -v209, v159, v203
	v_bfe_u32 v159, v203, 16, 1
	v_add3_u32 v203, v203, v159, s39
	global_store_short_d16_hi v[146:147], v203, off offset:2112
	v_mul_f32_e32 v160, v118, v164
	v_fma_f32 v204, -v209, v160, v204
	v_bfe_u32 v160, v204, 16, 1
	v_add3_u32 v204, v204, v160, s39
	global_store_short_d16_hi v[148:149], v204, off offset:64
	v_mul_f32_e32 v150, v119, v165
	v_fma_f32 v205, -v209, v150, v205
	v_bfe_u32 v150, v205, 16, 1
	v_add3_u32 v205, v205, v150, s39
	global_store_short_d16_hi v[148:149], v205, off offset:2112
	v_mul_f32_e32 v158, v100, v162
	v_fma_f32 v240, -v209, v158, v240
	v_bfe_u32 v158, v240, 16, 1
	v_add3_u32 v240, v240, v158, s39
	global_store_short_d16_hi v[146:147], v240, off offset:128
	v_mul_f32_e32 v159, v101, v163
	v_fma_f32 v241, -v209, v159, v241
	v_bfe_u32 v159, v241, 16, 1
	v_add3_u32 v241, v241, v159, s39
	global_store_short_d16_hi v[146:147], v241, off offset:2176
	v_mul_f32_e32 v160, v102, v164
	v_fma_f32 v242, -v209, v160, v242
	v_bfe_u32 v160, v242, 16, 1
	v_add3_u32 v242, v242, v160, s39
	global_store_short_d16_hi v[148:149], v242, off offset:128
	v_mul_f32_e32 v150, v103, v165
	v_fma_f32 v243, -v209, v150, v243
	v_bfe_u32 v150, v243, 16, 1
	v_add3_u32 v243, v243, v150, s39
	global_store_short_d16_hi v[148:149], v243, off offset:2176
	v_mul_f32_e32 v158, v84, v162
	v_fma_f32 v244, -v209, v158, v244
	v_bfe_u32 v158, v244, 16, 1
	v_add3_u32 v244, v244, v158, s39
	global_store_short_d16_hi v[146:147], v244, off offset:192
	v_mul_f32_e32 v159, v85, v163
	v_fma_f32 v245, -v209, v159, v245
	v_bfe_u32 v159, v245, 16, 1
	v_add3_u32 v245, v245, v159, s39
	global_store_short_d16_hi v[146:147], v245, off offset:2240
	v_mul_f32_e32 v160, v86, v164
	v_fma_f32 v246, -v209, v160, v246
	v_bfe_u32 v160, v246, 16, 1
	v_add3_u32 v246, v246, v160, s39
	global_store_short_d16_hi v[148:149], v246, off offset:192
	v_mul_f32_e32 v150, v87, v165
	v_fma_f32 v247, -v209, v150, v247
	v_bfe_u32 v150, v247, 16, 1
	v_add3_u32 v247, v247, v150, s39
	global_store_short_d16_hi v[148:149], v247, off offset:2240
	v_mul_f32_e32 v158, v68, v162
	v_fma_f32 v248, -v209, v158, v248
	v_bfe_u32 v158, v248, 16, 1
	v_add3_u32 v248, v248, v158, s39
	global_store_short_d16_hi v[146:147], v248, off offset:256
	v_mul_f32_e32 v159, v69, v163
	v_fma_f32 v249, -v209, v159, v249
	v_bfe_u32 v159, v249, 16, 1
	v_add3_u32 v249, v249, v159, s39
	global_store_short_d16_hi v[146:147], v249, off offset:2304
	v_mul_f32_e32 v160, v70, v164
	v_fma_f32 v250, -v209, v160, v250
	v_bfe_u32 v160, v250, 16, 1
	v_add3_u32 v250, v250, v160, s39
	global_store_short_d16_hi v[148:149], v250, off offset:256
	v_mul_f32_e32 v150, v71, v165
	v_fma_f32 v251, -v209, v150, v251
	v_bfe_u32 v150, v251, 16, 1
	v_add3_u32 v251, v251, v150, s39
	global_store_short_d16_hi v[148:149], v251, off offset:2304
	v_mul_f32_e32 v158, v52, v162
	v_fma_f32 v252, -v209, v158, v252
	v_bfe_u32 v158, v252, 16, 1
	v_add3_u32 v252, v252, v158, s39
	global_store_short_d16_hi v[146:147], v252, off offset:320
	v_mul_f32_e32 v159, v53, v163
	v_fma_f32 v253, -v209, v159, v253
	v_bfe_u32 v159, v253, 16, 1
	v_add3_u32 v253, v253, v159, s39
	global_store_short_d16_hi v[146:147], v253, off offset:2368
	v_mul_f32_e32 v160, v54, v164
	v_fma_f32 v254, -v209, v160, v254
	v_bfe_u32 v160, v254, 16, 1
	v_add3_u32 v254, v254, v160, s39
	global_store_short_d16_hi v[148:149], v254, off offset:320
	v_mul_f32_e32 v150, v55, v165
	v_fma_f32 v255, -v209, v150, v255
	v_bfe_u32 v150, v255, 16, 1
	v_add3_u32 v255, v255, v150, s39
	global_store_short_d16_hi v[148:149], v255, off offset:2368
	v_mul_f32_e32 v158, v36, v162
	v_fma_f32 v232, -v209, v158, v232
	v_bfe_u32 v158, v232, 16, 1
	v_add3_u32 v232, v232, v158, s39
	global_store_short_d16_hi v[146:147], v232, off offset:384
	v_mul_f32_e32 v159, v37, v163
	v_fma_f32 v233, -v209, v159, v233
	v_bfe_u32 v159, v233, 16, 1
	v_add3_u32 v233, v233, v159, s39
	global_store_short_d16_hi v[146:147], v233, off offset:2432
	v_mul_f32_e32 v160, v38, v164
	v_fma_f32 v234, -v209, v160, v234
	v_bfe_u32 v160, v234, 16, 1
	v_add3_u32 v234, v234, v160, s39
	global_store_short_d16_hi v[148:149], v234, off offset:384
	v_mul_f32_e32 v150, v39, v165
	v_fma_f32 v235, -v209, v150, v235
	v_bfe_u32 v150, v235, 16, 1
	v_add3_u32 v235, v235, v150, s39
	global_store_short_d16_hi v[148:149], v235, off offset:2432
	v_mul_f32_e32 v158, v20, v162
	v_fma_f32 v154, -v209, v158, v154
	v_bfe_u32 v158, v154, 16, 1
	v_add3_u32 v154, v154, v158, s39
	global_store_short_d16_hi v[146:147], v154, off offset:448
	v_mul_f32_e32 v159, v21, v163
	v_fma_f32 v155, -v209, v159, v155
	v_bfe_u32 v159, v155, 16, 1
	v_add3_u32 v155, v155, v159, s39
	global_store_short_d16_hi v[146:147], v155, off offset:2496
	v_mul_f32_e32 v160, v22, v164
	v_fma_f32 v156, -v209, v160, v156
	v_bfe_u32 v160, v156, 16, 1
	v_add3_u32 v156, v156, v160, s39
	global_store_short_d16_hi v[148:149], v156, off offset:448
	v_mul_f32_e32 v150, v23, v165
	v_fma_f32 v157, -v209, v150, v157
	v_bfe_u32 v150, v157, 16, 1
	v_add3_u32 v157, v157, v150, s39
	global_store_short_d16_hi v[148:149], v157, off offset:2496
	global_load_dwordx4 v[198:201], v128, s[96:97]
	s_add_u32 s96, s96, 0x1000
	s_addc_u32 s97, s97, 0
	global_load_dwordx4 v[202:205], v128, s[96:97]
	s_add_u32 s96, s96, 0x1000
	s_addc_u32 s97, s97, 0
	global_load_dwordx4 v[240:243], v128, s[96:97]
	s_add_u32 s96, s96, 0x1000
	s_addc_u32 s97, s97, 0
	global_load_dwordx4 v[244:247], v128, s[96:97]
	s_add_u32 s96, s96, 0x1000
	s_addc_u32 s97, s97, 0
	global_load_dwordx4 v[248:251], v128, s[96:97]
	s_add_u32 s96, s96, 0x1000
	s_addc_u32 s97, s97, 0
	global_load_dwordx4 v[252:255], v128, s[96:97]
	s_add_u32 s96, s96, 0x1000
	s_addc_u32 s97, s97, 0
	global_load_dwordx4 v[232:235], v128, s[96:97]
	s_add_u32 s96, s96, 0x1000
	s_addc_u32 s97, s97, 0
	global_load_dwordx4 v[154:157], v128, s[96:97]
	s_add_u32 s96, s96, 0x1000
	s_addc_u32 s97, s97, 0
	v_lshl_add_u64 v[146:147], v[146:147], 0, s[98:99]
	s_waitcnt vmcnt(40)
	v_lshl_add_u64 v[148:149], v[146:147], 0, s[100:101]
	v_mul_f32_e32 v158, v8, v137
	v_fma_f32 v166, -v209, v158, v166
	v_bfe_u32 v158, v166, 16, 1
	v_add3_u32 v166, v166, v158, s39
	global_store_short_d16_hi v[146:147], v166, off
	v_mul_f32_e32 v159, v9, v136
	v_fma_f32 v167, -v209, v159, v167
	v_bfe_u32 v159, v167, 16, 1
	v_add3_u32 v167, v167, v159, s39
	global_store_short_d16_hi v[146:147], v167, off offset:2048
	v_mul_f32_e32 v160, v10, v135
	v_fma_f32 v168, -v209, v160, v168
	v_bfe_u32 v160, v168, 16, 1
	v_add3_u32 v168, v168, v160, s39
	global_store_short_d16_hi v[148:149], v168, off
	v_mul_f32_e32 v150, v11, v134
	v_fma_f32 v169, -v209, v150, v169
	v_bfe_u32 v150, v169, 16, 1
	v_add3_u32 v169, v169, v150, s39
	global_store_short_d16_hi v[148:149], v169, off offset:2048
	v_mul_f32_e32 v158, v120, v137
	v_fma_f32 v170, -v209, v158, v170
	v_bfe_u32 v158, v170, 16, 1
	v_add3_u32 v170, v170, v158, s39
	global_store_short_d16_hi v[146:147], v170, off offset:64
	v_mul_f32_e32 v159, v121, v136
	v_fma_f32 v171, -v209, v159, v171
	v_bfe_u32 v159, v171, 16, 1
	v_add3_u32 v171, v171, v159, s39
	global_store_short_d16_hi v[146:147], v171, off offset:2112
	v_mul_f32_e32 v160, v122, v135
	v_fma_f32 v172, -v209, v160, v172
	v_bfe_u32 v160, v172, 16, 1
	v_add3_u32 v172, v172, v160, s39
	global_store_short_d16_hi v[148:149], v172, off offset:64
	v_mul_f32_e32 v150, v123, v134
	v_fma_f32 v173, -v209, v150, v173
	v_bfe_u32 v150, v173, 16, 1
	v_add3_u32 v173, v173, v150, s39
	global_store_short_d16_hi v[148:149], v173, off offset:2112
	v_mul_f32_e32 v158, v104, v137
	v_fma_f32 v174, -v209, v158, v174
	v_bfe_u32 v158, v174, 16, 1
	v_add3_u32 v174, v174, v158, s39
	global_store_short_d16_hi v[146:147], v174, off offset:128
	v_mul_f32_e32 v159, v105, v136
	v_fma_f32 v175, -v209, v159, v175
	v_bfe_u32 v159, v175, 16, 1
	v_add3_u32 v175, v175, v159, s39
	global_store_short_d16_hi v[146:147], v175, off offset:2176
	v_mul_f32_e32 v160, v106, v135
	v_fma_f32 v176, -v209, v160, v176
	v_bfe_u32 v160, v176, 16, 1
	v_add3_u32 v176, v176, v160, s39
	global_store_short_d16_hi v[148:149], v176, off offset:128
	v_mul_f32_e32 v150, v107, v134
	v_fma_f32 v177, -v209, v150, v177
	v_bfe_u32 v150, v177, 16, 1
	v_add3_u32 v177, v177, v150, s39
	global_store_short_d16_hi v[148:149], v177, off offset:2176
	v_mul_f32_e32 v158, v88, v137
	v_fma_f32 v178, -v209, v158, v178
	v_bfe_u32 v158, v178, 16, 1
	v_add3_u32 v178, v178, v158, s39
	global_store_short_d16_hi v[146:147], v178, off offset:192
	v_mul_f32_e32 v159, v89, v136
	v_fma_f32 v179, -v209, v159, v179
	v_bfe_u32 v159, v179, 16, 1
	v_add3_u32 v179, v179, v159, s39
	global_store_short_d16_hi v[146:147], v179, off offset:2240
	v_mul_f32_e32 v160, v90, v135
	v_fma_f32 v180, -v209, v160, v180
	v_bfe_u32 v160, v180, 16, 1
	v_add3_u32 v180, v180, v160, s39
	global_store_short_d16_hi v[148:149], v180, off offset:192
	v_mul_f32_e32 v150, v91, v134
	v_fma_f32 v181, -v209, v150, v181
	v_bfe_u32 v150, v181, 16, 1
	v_add3_u32 v181, v181, v150, s39
	global_store_short_d16_hi v[148:149], v181, off offset:2240
	v_mul_f32_e32 v158, v72, v137
	v_fma_f32 v182, -v209, v158, v182
	v_bfe_u32 v158, v182, 16, 1
	v_add3_u32 v182, v182, v158, s39
	global_store_short_d16_hi v[146:147], v182, off offset:256
	v_mul_f32_e32 v159, v73, v136
	v_fma_f32 v183, -v209, v159, v183
	v_bfe_u32 v159, v183, 16, 1
	v_add3_u32 v183, v183, v159, s39
	global_store_short_d16_hi v[146:147], v183, off offset:2304
	v_mul_f32_e32 v160, v74, v135
	v_fma_f32 v184, -v209, v160, v184
	v_bfe_u32 v160, v184, 16, 1
	v_add3_u32 v184, v184, v160, s39
	global_store_short_d16_hi v[148:149], v184, off offset:256
	v_mul_f32_e32 v150, v75, v134
	v_fma_f32 v185, -v209, v150, v185
	v_bfe_u32 v150, v185, 16, 1
	v_add3_u32 v185, v185, v150, s39
	global_store_short_d16_hi v[148:149], v185, off offset:2304
	v_mul_f32_e32 v158, v56, v137
	v_fma_f32 v186, -v209, v158, v186
	v_bfe_u32 v158, v186, 16, 1
	v_add3_u32 v186, v186, v158, s39
	global_store_short_d16_hi v[146:147], v186, off offset:320
	v_mul_f32_e32 v159, v57, v136
	v_fma_f32 v187, -v209, v159, v187
	v_bfe_u32 v159, v187, 16, 1
	v_add3_u32 v187, v187, v159, s39
	global_store_short_d16_hi v[146:147], v187, off offset:2368
	v_mul_f32_e32 v160, v58, v135
	v_fma_f32 v188, -v209, v160, v188
	v_bfe_u32 v160, v188, 16, 1
	v_add3_u32 v188, v188, v160, s39
	global_store_short_d16_hi v[148:149], v188, off offset:320
	v_mul_f32_e32 v150, v59, v134
	v_fma_f32 v189, -v209, v150, v189
	v_bfe_u32 v150, v189, 16, 1
	v_add3_u32 v189, v189, v150, s39
	global_store_short_d16_hi v[148:149], v189, off offset:2368
	v_mul_f32_e32 v158, v40, v137
	v_fma_f32 v190, -v209, v158, v190
	v_bfe_u32 v158, v190, 16, 1
	v_add3_u32 v190, v190, v158, s39
	global_store_short_d16_hi v[146:147], v190, off offset:384
	v_mul_f32_e32 v159, v41, v136
	v_fma_f32 v191, -v209, v159, v191
	v_bfe_u32 v159, v191, 16, 1
	v_add3_u32 v191, v191, v159, s39
	global_store_short_d16_hi v[146:147], v191, off offset:2432
	v_mul_f32_e32 v160, v42, v135
	v_fma_f32 v192, -v209, v160, v192
	v_bfe_u32 v160, v192, 16, 1
	v_add3_u32 v192, v192, v160, s39
	global_store_short_d16_hi v[148:149], v192, off offset:384
	v_mul_f32_e32 v150, v43, v134
	v_fma_f32 v193, -v209, v150, v193
	v_bfe_u32 v150, v193, 16, 1
	v_add3_u32 v193, v193, v150, s39
	global_store_short_d16_hi v[148:149], v193, off offset:2432
	v_mul_f32_e32 v158, v24, v137
	v_fma_f32 v194, -v209, v158, v194
	v_bfe_u32 v158, v194, 16, 1
	v_add3_u32 v194, v194, v158, s39
	global_store_short_d16_hi v[146:147], v194, off offset:448
	v_mul_f32_e32 v159, v25, v136
	v_fma_f32 v195, -v209, v159, v195
	v_bfe_u32 v159, v195, 16, 1
	v_add3_u32 v195, v195, v159, s39
	global_store_short_d16_hi v[146:147], v195, off offset:2496
	v_mul_f32_e32 v160, v26, v135
	v_fma_f32 v196, -v209, v160, v196
	v_bfe_u32 v160, v196, 16, 1
	v_add3_u32 v196, v196, v160, s39
	global_store_short_d16_hi v[148:149], v196, off offset:448
	v_mul_f32_e32 v150, v27, v134
	v_fma_f32 v197, -v209, v150, v197
	v_bfe_u32 v150, v197, 16, 1
	v_add3_u32 v197, v197, v150, s39
	global_store_short_d16_hi v[148:149], v197, off offset:2496
	v_lshl_add_u64 v[146:147], v[146:147], 0, s[98:99]
	s_waitcnt vmcnt(32)
	v_lshl_add_u64 v[148:149], v[146:147], 0, s[100:101]
	v_mul_f32_e32 v158, v12, v133
	v_fma_f32 v198, -v209, v158, v198
	v_bfe_u32 v158, v198, 16, 1
	v_add3_u32 v198, v198, v158, s39
	global_store_short_d16_hi v[146:147], v198, off
	v_mul_f32_e32 v159, v13, v132
	v_fma_f32 v199, -v209, v159, v199
	v_bfe_u32 v159, v199, 16, 1
	v_add3_u32 v199, v199, v159, s39
	global_store_short_d16_hi v[146:147], v199, off offset:2048
	v_mul_f32_e32 v160, v14, v131
	v_fma_f32 v200, -v209, v160, v200
	v_bfe_u32 v160, v200, 16, 1
	v_add3_u32 v200, v200, v160, s39
	global_store_short_d16_hi v[148:149], v200, off
	v_mul_f32_e32 v150, v15, v130
	v_fma_f32 v201, -v209, v150, v201
	v_bfe_u32 v150, v201, 16, 1
	v_add3_u32 v201, v201, v150, s39
	global_store_short_d16_hi v[148:149], v201, off offset:2048
	v_mul_f32_e32 v158, v124, v133
	v_fma_f32 v202, -v209, v158, v202
	v_bfe_u32 v158, v202, 16, 1
	v_add3_u32 v202, v202, v158, s39
	global_store_short_d16_hi v[146:147], v202, off offset:64
	v_mul_f32_e32 v159, v125, v132
	v_fma_f32 v203, -v209, v159, v203
	v_bfe_u32 v159, v203, 16, 1
	v_add3_u32 v203, v203, v159, s39
	global_store_short_d16_hi v[146:147], v203, off offset:2112
	v_mul_f32_e32 v160, v126, v131
	v_fma_f32 v204, -v209, v160, v204
	v_bfe_u32 v160, v204, 16, 1
	v_add3_u32 v204, v204, v160, s39
	global_store_short_d16_hi v[148:149], v204, off offset:64
	v_mul_f32_e32 v150, v127, v130
	v_fma_f32 v205, -v209, v150, v205
	v_bfe_u32 v150, v205, 16, 1
	v_add3_u32 v205, v205, v150, s39
	global_store_short_d16_hi v[148:149], v205, off offset:2112
	v_mul_f32_e32 v158, v108, v133
	v_fma_f32 v240, -v209, v158, v240
	v_bfe_u32 v158, v240, 16, 1
	v_add3_u32 v240, v240, v158, s39
	global_store_short_d16_hi v[146:147], v240, off offset:128
	v_mul_f32_e32 v159, v109, v132
	v_fma_f32 v241, -v209, v159, v241
	v_bfe_u32 v159, v241, 16, 1
	v_add3_u32 v241, v241, v159, s39
	global_store_short_d16_hi v[146:147], v241, off offset:2176
	v_mul_f32_e32 v160, v110, v131
	v_fma_f32 v242, -v209, v160, v242
	v_bfe_u32 v160, v242, 16, 1
	v_add3_u32 v242, v242, v160, s39
	global_store_short_d16_hi v[148:149], v242, off offset:128
	v_mul_f32_e32 v150, v111, v130
	v_fma_f32 v243, -v209, v150, v243
	v_bfe_u32 v150, v243, 16, 1
	v_add3_u32 v243, v243, v150, s39
	global_store_short_d16_hi v[148:149], v243, off offset:2176
	v_mul_f32_e32 v158, v92, v133
	v_fma_f32 v244, -v209, v158, v244
	v_bfe_u32 v158, v244, 16, 1
	v_add3_u32 v244, v244, v158, s39
	global_store_short_d16_hi v[146:147], v244, off offset:192
	v_mul_f32_e32 v159, v93, v132
	v_fma_f32 v245, -v209, v159, v245
	v_bfe_u32 v159, v245, 16, 1
	v_add3_u32 v245, v245, v159, s39
	global_store_short_d16_hi v[146:147], v245, off offset:2240
	v_mul_f32_e32 v160, v94, v131
	v_fma_f32 v246, -v209, v160, v246
	v_bfe_u32 v160, v246, 16, 1
	v_add3_u32 v246, v246, v160, s39
	global_store_short_d16_hi v[148:149], v246, off offset:192
	v_mul_f32_e32 v150, v95, v130
	v_fma_f32 v247, -v209, v150, v247
	v_bfe_u32 v150, v247, 16, 1
	v_add3_u32 v247, v247, v150, s39
	global_store_short_d16_hi v[148:149], v247, off offset:2240
	v_mul_f32_e32 v158, v76, v133
	v_fma_f32 v248, -v209, v158, v248
	v_bfe_u32 v158, v248, 16, 1
	v_add3_u32 v248, v248, v158, s39
	global_store_short_d16_hi v[146:147], v248, off offset:256
	v_mul_f32_e32 v159, v77, v132
	v_fma_f32 v249, -v209, v159, v249
	v_bfe_u32 v159, v249, 16, 1
	v_add3_u32 v249, v249, v159, s39
	global_store_short_d16_hi v[146:147], v249, off offset:2304
	v_mul_f32_e32 v160, v78, v131
	v_fma_f32 v250, -v209, v160, v250
	v_bfe_u32 v160, v250, 16, 1
	v_add3_u32 v250, v250, v160, s39
	global_store_short_d16_hi v[148:149], v250, off offset:256
	v_mul_f32_e32 v150, v79, v130
	v_fma_f32 v251, -v209, v150, v251
	v_bfe_u32 v150, v251, 16, 1
	v_add3_u32 v251, v251, v150, s39
	global_store_short_d16_hi v[148:149], v251, off offset:2304
	v_mul_f32_e32 v158, v60, v133
	v_fma_f32 v252, -v209, v158, v252
	v_bfe_u32 v158, v252, 16, 1
	v_add3_u32 v252, v252, v158, s39
	global_store_short_d16_hi v[146:147], v252, off offset:320
	v_mul_f32_e32 v159, v61, v132
	v_fma_f32 v253, -v209, v159, v253
	v_bfe_u32 v159, v253, 16, 1
	v_add3_u32 v253, v253, v159, s39
	global_store_short_d16_hi v[146:147], v253, off offset:2368
	v_mul_f32_e32 v160, v62, v131
	v_fma_f32 v254, -v209, v160, v254
	v_bfe_u32 v160, v254, 16, 1
	v_add3_u32 v254, v254, v160, s39
	global_store_short_d16_hi v[148:149], v254, off offset:320
	v_mul_f32_e32 v150, v63, v130
	v_fma_f32 v255, -v209, v150, v255
	v_bfe_u32 v150, v255, 16, 1
	v_add3_u32 v255, v255, v150, s39
	global_store_short_d16_hi v[148:149], v255, off offset:2368
	v_mul_f32_e32 v158, v44, v133
	v_fma_f32 v232, -v209, v158, v232
	v_bfe_u32 v158, v232, 16, 1
	v_add3_u32 v232, v232, v158, s39
	global_store_short_d16_hi v[146:147], v232, off offset:384
	v_mul_f32_e32 v159, v45, v132
	v_fma_f32 v233, -v209, v159, v233
	v_bfe_u32 v159, v233, 16, 1
	v_add3_u32 v233, v233, v159, s39
	global_store_short_d16_hi v[146:147], v233, off offset:2432
	v_mul_f32_e32 v160, v46, v131
	v_fma_f32 v234, -v209, v160, v234
	v_bfe_u32 v160, v234, 16, 1
	v_add3_u32 v234, v234, v160, s39
	global_store_short_d16_hi v[148:149], v234, off offset:384
	v_mul_f32_e32 v150, v47, v130
	v_fma_f32 v235, -v209, v150, v235
	v_bfe_u32 v150, v235, 16, 1
	v_add3_u32 v235, v235, v150, s39
	global_store_short_d16_hi v[148:149], v235, off offset:2432
	v_mul_f32_e32 v158, v28, v133
	v_fma_f32 v154, -v209, v158, v154
	v_bfe_u32 v158, v154, 16, 1
	v_add3_u32 v154, v154, v158, s39
	global_store_short_d16_hi v[146:147], v154, off offset:448
	v_mul_f32_e32 v159, v29, v132
	v_fma_f32 v155, -v209, v159, v155
	v_bfe_u32 v159, v155, 16, 1
	v_add3_u32 v155, v155, v159, s39
	global_store_short_d16_hi v[146:147], v155, off offset:2496
	v_mul_f32_e32 v160, v30, v131
	v_fma_f32 v156, -v209, v160, v156
	v_bfe_u32 v160, v156, 16, 1
	v_add3_u32 v156, v156, v160, s39
	global_store_short_d16_hi v[148:149], v156, off offset:448
	v_mul_f32_e32 v150, v31, v130
	v_fma_f32 v157, -v209, v150, v157
	v_bfe_u32 v150, v157, 16, 1
	v_add3_u32 v157, v157, v150, s39
	global_store_short_d16_hi v[148:149], v157, off offset:2496
	s_branch .LBB0_508
.Lepi0_p0:
	v_mul_f32_e32 v166, v0, v142
	v_mul_f32_e32 v167, v1, v145
	v_mul_f32_e32 v168, v2, v152
	v_mul_f32_e32 v169, v3, v161
	global_store_dwordx4 v128, v[166:169], s[96:97]
	s_add_u32 s96, s96, 0x1000
	s_addc_u32 s97, s97, 0
	v_mul_f32_e32 v170, v112, v142
	v_mul_f32_e32 v171, v113, v145
	v_mul_f32_e32 v172, v114, v152
	v_mul_f32_e32 v173, v115, v161
	global_store_dwordx4 v128, v[170:173], s[96:97]
	s_add_u32 s96, s96, 0x1000
	s_addc_u32 s97, s97, 0
	v_mul_f32_e32 v174, v96, v142
	v_mul_f32_e32 v175, v97, v145
	v_mul_f32_e32 v176, v98, v152
	v_mul_f32_e32 v177, v99, v161
	global_store_dwordx4 v128, v[174:177], s[96:97]
	s_add_u32 s96, s96, 0x1000
	s_addc_u32 s97, s97, 0
	v_mul_f32_e32 v178, v80, v142
	v_mul_f32_e32 v179, v81, v145
	v_mul_f32_e32 v180, v82, v152
	v_mul_f32_e32 v181, v83, v161
	global_store_dwordx4 v128, v[178:181], s[96:97]
	s_add_u32 s96, s96, 0x1000
	s_addc_u32 s97, s97, 0
	v_mul_f32_e32 v182, v64, v142
	v_mul_f32_e32 v183, v65, v145
	v_mul_f32_e32 v184, v66, v152
	v_mul_f32_e32 v185, v67, v161
	global_store_dwordx4 v128, v[182:185], s[96:97]
	s_add_u32 s96, s96, 0x1000
	s_addc_u32 s97, s97, 0
	v_mul_f32_e32 v186, v48, v142
	v_mul_f32_e32 v187, v49, v145
	v_mul_f32_e32 v188, v50, v152
	v_mul_f32_e32 v189, v51, v161
	global_store_dwordx4 v128, v[186:189], s[96:97]
	s_add_u32 s96, s96, 0x1000
	s_addc_u32 s97, s97, 0
	v_mul_f32_e32 v190, v32, v142
	v_mul_f32_e32 v191, v33, v145
	v_mul_f32_e32 v192, v34, v152
	v_mul_f32_e32 v193, v35, v161
	global_store_dwordx4 v128, v[190:193], s[96:97]
	s_add_u32 s96, s96, 0x1000
	s_addc_u32 s97, s97, 0
	v_mul_f32_e32 v194, v16, v142
	v_mul_f32_e32 v195, v17, v145
	v_mul_f32_e32 v196, v18, v152
	v_mul_f32_e32 v197, v19, v161
	global_store_dwordx4 v128, v[194:197], s[96:97]
	s_add_u32 s96, s96, 0x1000
	s_addc_u32 s97, s97, 0
	v_mul_f32_e32 v198, v4, v162
	v_mul_f32_e32 v199, v5, v163
	v_mul_f32_e32 v200, v6, v164
	v_mul_f32_e32 v201, v7, v165
	global_store_dwordx4 v128, v[198:201], s[96:97]
	s_add_u32 s96, s96, 0x1000
	s_addc_u32 s97, s97, 0
	v_mul_f32_e32 v202, v116, v162
	v_mul_f32_e32 v203, v117, v163
	v_mul_f32_e32 v204, v118, v164
	v_mul_f32_e32 v205, v119, v165
	global_store_dwordx4 v128, v[202:205], s[96:97]
	s_add_u32 s96, s96, 0x1000
	s_addc_u32 s97, s97, 0
	v_mul_f32_e32 v240, v100, v162
	v_mul_f32_e32 v241, v101, v163
	v_mul_f32_e32 v242, v102, v164
	v_mul_f32_e32 v243, v103, v165
	global_store_dwordx4 v128, v[240:243], s[96:97]
	s_add_u32 s96, s96, 0x1000
	s_addc_u32 s97, s97, 0
	v_mul_f32_e32 v244, v84, v162
	v_mul_f32_e32 v245, v85, v163
	v_mul_f32_e32 v246, v86, v164
	v_mul_f32_e32 v247, v87, v165
	global_store_dwordx4 v128, v[244:247], s[96:97]
	s_add_u32 s96, s96, 0x1000
	s_addc_u32 s97, s97, 0
	v_mul_f32_e32 v248, v68, v162
	v_mul_f32_e32 v249, v69, v163
	v_mul_f32_e32 v250, v70, v164
	v_mul_f32_e32 v251, v71, v165
	global_store_dwordx4 v128, v[248:251], s[96:97]
	s_add_u32 s96, s96, 0x1000
	s_addc_u32 s97, s97, 0
	v_mul_f32_e32 v252, v52, v162
	v_mul_f32_e32 v253, v53, v163
	v_mul_f32_e32 v254, v54, v164
	v_mul_f32_e32 v255, v55, v165
	global_store_dwordx4 v128, v[252:255], s[96:97]
	s_add_u32 s96, s96, 0x1000
	s_addc_u32 s97, s97, 0
	v_mul_f32_e32 v232, v36, v162
	v_mul_f32_e32 v233, v37, v163
	v_mul_f32_e32 v234, v38, v164
	v_mul_f32_e32 v235, v39, v165
	global_store_dwordx4 v128, v[232:235], s[96:97]
	s_add_u32 s96, s96, 0x1000
	s_addc_u32 s97, s97, 0
	v_mul_f32_e32 v154, v20, v162
	v_mul_f32_e32 v155, v21, v163
	v_mul_f32_e32 v156, v22, v164
	v_mul_f32_e32 v157, v23, v165
	global_store_dwordx4 v128, v[154:157], s[96:97]
	s_add_u32 s96, s96, 0x1000
	s_addc_u32 s97, s97, 0
	v_mul_f32_e32 v166, v8, v137
	v_mul_f32_e32 v167, v9, v136
	v_mul_f32_e32 v168, v10, v135
	v_mul_f32_e32 v169, v11, v134
	global_store_dwordx4 v128, v[166:169], s[96:97]
	s_add_u32 s96, s96, 0x1000
	s_addc_u32 s97, s97, 0
	v_mul_f32_e32 v170, v120, v137
	v_mul_f32_e32 v171, v121, v136
	v_mul_f32_e32 v172, v122, v135
	v_mul_f32_e32 v173, v123, v134
	global_store_dwordx4 v128, v[170:173], s[96:97]
	s_add_u32 s96, s96, 0x1000
	s_addc_u32 s97, s97, 0
	v_mul_f32_e32 v174, v104, v137
	v_mul_f32_e32 v175, v105, v136
	v_mul_f32_e32 v176, v106, v135
	v_mul_f32_e32 v177, v107, v134
	global_store_dwordx4 v128, v[174:177], s[96:97]
	s_add_u32 s96, s96, 0x1000
	s_addc_u32 s97, s97, 0
	v_mul_f32_e32 v178, v88, v137
	v_mul_f32_e32 v179, v89, v136
	v_mul_f32_e32 v180, v90, v135
	v_mul_f32_e32 v181, v91, v134
	global_store_dwordx4 v128, v[178:181], s[96:97]
	s_add_u32 s96, s96, 0x1000
	s_addc_u32 s97, s97, 0
	v_mul_f32_e32 v182, v72, v137
	v_mul_f32_e32 v183, v73, v136
	v_mul_f32_e32 v184, v74, v135
	v_mul_f32_e32 v185, v75, v134
	global_store_dwordx4 v128, v[182:185], s[96:97]
	s_add_u32 s96, s96, 0x1000
	s_addc_u32 s97, s97, 0
	v_mul_f32_e32 v186, v56, v137
	v_mul_f32_e32 v187, v57, v136
	v_mul_f32_e32 v188, v58, v135
	v_mul_f32_e32 v189, v59, v134
	global_store_dwordx4 v128, v[186:189], s[96:97]
	s_add_u32 s96, s96, 0x1000
	s_addc_u32 s97, s97, 0
	v_mul_f32_e32 v190, v40, v137
	v_mul_f32_e32 v191, v41, v136
	v_mul_f32_e32 v192, v42, v135
	v_mul_f32_e32 v193, v43, v134
	global_store_dwordx4 v128, v[190:193], s[96:97]
	s_add_u32 s96, s96, 0x1000
	s_addc_u32 s97, s97, 0
	v_mul_f32_e32 v194, v24, v137
	v_mul_f32_e32 v195, v25, v136
	v_mul_f32_e32 v196, v26, v135
	v_mul_f32_e32 v197, v27, v134
	global_store_dwordx4 v128, v[194:197], s[96:97]
	s_add_u32 s96, s96, 0x1000
	s_addc_u32 s97, s97, 0
	v_mul_f32_e32 v198, v12, v133
	v_mul_f32_e32 v199, v13, v132
	v_mul_f32_e32 v200, v14, v131
	v_mul_f32_e32 v201, v15, v130
	global_store_dwordx4 v128, v[198:201], s[96:97]
	s_add_u32 s96, s96, 0x1000
	s_addc_u32 s97, s97, 0
	v_mul_f32_e32 v202, v124, v133
	v_mul_f32_e32 v203, v125, v132
	v_mul_f32_e32 v204, v126, v131
	v_mul_f32_e32 v205, v127, v130
	global_store_dwordx4 v128, v[202:205], s[96:97]
	s_add_u32 s96, s96, 0x1000
	s_addc_u32 s97, s97, 0
	v_mul_f32_e32 v240, v108, v133
	v_mul_f32_e32 v241, v109, v132
	v_mul_f32_e32 v242, v110, v131
	v_mul_f32_e32 v243, v111, v130
	global_store_dwordx4 v128, v[240:243], s[96:97]
	s_add_u32 s96, s96, 0x1000
	s_addc_u32 s97, s97, 0
	v_mul_f32_e32 v244, v92, v133
	v_mul_f32_e32 v245, v93, v132
	v_mul_f32_e32 v246, v94, v131
	v_mul_f32_e32 v247, v95, v130
	global_store_dwordx4 v128, v[244:247], s[96:97]
	s_add_u32 s96, s96, 0x1000
	s_addc_u32 s97, s97, 0
	v_mul_f32_e32 v248, v76, v133
	v_mul_f32_e32 v249, v77, v132
	v_mul_f32_e32 v250, v78, v131
	v_mul_f32_e32 v251, v79, v130
	global_store_dwordx4 v128, v[248:251], s[96:97]
	s_add_u32 s96, s96, 0x1000
	s_addc_u32 s97, s97, 0
	v_mul_f32_e32 v252, v60, v133
	v_mul_f32_e32 v253, v61, v132
	v_mul_f32_e32 v254, v62, v131
	v_mul_f32_e32 v255, v63, v130
	global_store_dwordx4 v128, v[252:255], s[96:97]
	s_add_u32 s96, s96, 0x1000
	s_addc_u32 s97, s97, 0
	v_mul_f32_e32 v232, v44, v133
	v_mul_f32_e32 v233, v45, v132
	v_mul_f32_e32 v234, v46, v131
	v_mul_f32_e32 v235, v47, v130
	global_store_dwordx4 v128, v[232:235], s[96:97]
	s_add_u32 s96, s96, 0x1000
	s_addc_u32 s97, s97, 0
	v_mul_f32_e32 v154, v28, v133
	v_mul_f32_e32 v155, v29, v132
	v_mul_f32_e32 v156, v30, v131
	v_mul_f32_e32 v157, v31, v130
	global_store_dwordx4 v128, v[154:157], s[96:97]
	s_add_u32 s96, s96, 0x1000
	s_addc_u32 s97, s97, 0
	s_branch .LBB0_508

.LBB0_914:
	s_and_saveexec_b64 s[4:5], s[0:1]
	ds_write_b32 v224, v144
	s_or_b64 exec, exec, s[4:5]
	s_waitcnt lgkmcnt(0)
	v_add_u32_e32 v136, s21, v210
	ds_read_b128 v[128:131], v136
	ds_read_b128 v[132:135], v136 offset:32
	s_ashr_i32 s21, s20, 31
	s_lshl_b64 s[0:1], s[20:21], 12
	ds_read_b128 v[138:141], v136 offset:96
	s_waitcnt lgkmcnt(2)
	v_rcp_f32_e32 v142, v128
	v_rcp_f32_e32 v145, v129
	v_rcp_f32_e32 v152, v130
	v_rcp_f32_e32 v161, v131
	ds_read_b128 v[128:131], v136 offset:64
	s_waitcnt lgkmcnt(2)
	v_rcp_f32_e32 v162, v132
	v_rcp_f32_e32 v163, v133
	v_rcp_f32_e32 v164, v134
	v_rcp_f32_e32 v165, v135
	s_waitcnt lgkmcnt(0)
	v_rcp_f32_e32 v137, v128
	v_rcp_f32_e32 v136, v129
	v_rcp_f32_e32 v135, v130
	v_rcp_f32_e32 v134, v131
	v_rcp_f32_e32 v133, v138
	v_rcp_f32_e32 v132, v139
	v_rcp_f32_e32 v131, v140
	v_rcp_f32_e32 v130, v141
	s_add_u32 s0, s66, s0
	s_addc_u32 s1, s67, s1
	s_mov_b64 s[4:5], -1
	s_andn2_b64 vcc, exec, s[18:19]
	v_lshlrev_b32_e32 v210, 2, v219
	v_lshlrev_b32_e32 v128, 14, v218
	v_lshl_add_u32 v129, v218, 5, v219
	v_lshlrev_b32_e32 v128, 4, v129
	s_mov_b32 s96, s0
	s_mov_b32 s97, s1
	s_cbranch_vccnz .Lepi1_p0
	s_lshl_b64 s[4:5], s[20:21], 11
	s_add_u32 s4, s68, s4
	s_addc_u32 s5, s69, s5
	v_lshlrev_b32_e32 v140, 1, v219
	v_lshl_add_u32 v140, v218, 13, v140
	v_mov_b32_e32 v141, 0
	v_lshl_add_u64 v[146:147], s[4:5], 0, v[140:141]
	s_mov_b64 s[100:101], 0x1000
	s_mov_b64 s[98:99], 0x4000
	global_load_dwordx4 v[166:169], v128, s[96:97]
	s_add_u32 s96, s96, 0x1000
	s_addc_u32 s97, s97, 0
	global_load_dwordx4 v[170:173], v128, s[96:97]
	s_add_u32 s96, s96, 0x1000
	s_addc_u32 s97, s97, 0
	global_load_dwordx4 v[174:177], v128, s[96:97]
	s_add_u32 s96, s96, 0x1000
	s_addc_u32 s97, s97, 0
	global_load_dwordx4 v[178:181], v128, s[96:97]
	s_add_u32 s96, s96, 0x1000
	s_addc_u32 s97, s97, 0
	global_load_dwordx4 v[182:185], v128, s[96:97]
	s_add_u32 s96, s96, 0x1000
	s_addc_u32 s97, s97, 0
	global_load_dwordx4 v[186:189], v128, s[96:97]
	s_add_u32 s96, s96, 0x1000
	s_addc_u32 s97, s97, 0
	global_load_dwordx4 v[190:193], v128, s[96:97]
	s_add_u32 s96, s96, 0x1000
	s_addc_u32 s97, s97, 0
	global_load_dwordx4 v[194:197], v128, s[96:97]
	s_add_u32 s96, s96, 0x1000
	s_addc_u32 s97, s97, 0
	global_load_dwordx4 v[198:201], v128, s[96:97]
	s_add_u32 s96, s96, 0x1000
	s_addc_u32 s97, s97, 0
	global_load_dwordx4 v[202:205], v128, s[96:97]
	s_add_u32 s96, s96, 0x1000
	s_addc_u32 s97, s97, 0
	global_load_dwordx4 v[240:243], v128, s[96:97]
	s_add_u32 s96, s96, 0x1000
	s_addc_u32 s97, s97, 0
	global_load_dwordx4 v[244:247], v128, s[96:97]
	s_add_u32 s96, s96, 0x1000
	s_addc_u32 s97, s97, 0
	global_load_dwordx4 v[248:251], v128, s[96:97]
	s_add_u32 s96, s96, 0x1000
	s_addc_u32 s97, s97, 0
	global_load_dwordx4 v[252:255], v128, s[96:97]
	s_add_u32 s96, s96, 0x1000
	s_addc_u32 s97, s97, 0
	global_load_dwordx4 v[232:235], v128, s[96:97]
	s_add_u32 s96, s96, 0x1000
	s_addc_u32 s97, s97, 0
	global_load_dwordx4 v[154:157], v128, s[96:97]
	s_add_u32 s96, s96, 0x1000
	s_addc_u32 s97, s97, 0
	s_waitcnt vmcnt(8)
	v_lshl_add_u64 v[148:149], v[146:147], 0, s[100:101]
	v_mul_f32_e32 v158, v0, v142
	v_fma_f32 v166, -v209, v158, v166
	v_bfe_u32 v158, v166, 16, 1
	v_add3_u32 v166, v166, v158, s43
	global_store_short_d16_hi v[146:147], v166, off
	v_mul_f32_e32 v159, v1, v145
	v_fma_f32 v167, -v209, v159, v167
	v_bfe_u32 v159, v167, 16, 1
	v_add3_u32 v167, v167, v159, s43
	global_store_short_d16_hi v[146:147], v167, off offset:2048
	v_mul_f32_e32 v160, v2, v152
	v_fma_f32 v168, -v209, v160, v168
	v_bfe_u32 v160, v168, 16, 1
	v_add3_u32 v168, v168, v160, s43
	global_store_short_d16_hi v[148:149], v168, off
	v_mul_f32_e32 v150, v3, v161
	v_fma_f32 v169, -v209, v150, v169
	v_bfe_u32 v150, v169, 16, 1
	v_add3_u32 v169, v169, v150, s43
	global_store_short_d16_hi v[148:149], v169, off offset:2048
	v_mul_f32_e32 v158, v112, v142
	v_fma_f32 v170, -v209, v158, v170
	v_bfe_u32 v158, v170, 16, 1
	v_add3_u32 v170, v170, v158, s43
	global_store_short_d16_hi v[146:147], v170, off offset:64
	v_mul_f32_e32 v159, v113, v145
	v_fma_f32 v171, -v209, v159, v171
	v_bfe_u32 v159, v171, 16, 1
	v_add3_u32 v171, v171, v159, s43
	global_store_short_d16_hi v[146:147], v171, off offset:2112
	v_mul_f32_e32 v160, v114, v152
	v_fma_f32 v172, -v209, v160, v172
	v_bfe_u32 v160, v172, 16, 1
	v_add3_u32 v172, v172, v160, s43
	global_store_short_d16_hi v[148:149], v172, off offset:64
	v_mul_f32_e32 v150, v115, v161
	v_fma_f32 v173, -v209, v150, v173
	v_bfe_u32 v150, v173, 16, 1
	v_add3_u32 v173, v173, v150, s43
	global_store_short_d16_hi v[148:149], v173, off offset:2112
	v_mul_f32_e32 v158, v96, v142
	v_fma_f32 v174, -v209, v158, v174
	v_bfe_u32 v158, v174, 16, 1
	v_add3_u32 v174, v174, v158, s43
	global_store_short_d16_hi v[146:147], v174, off offset:128
	v_mul_f32_e32 v159, v97, v145
	v_fma_f32 v175, -v209, v159, v175
	v_bfe_u32 v159, v175, 16, 1
	v_add3_u32 v175, v175, v159, s43
	global_store_short_d16_hi v[146:147], v175, off offset:2176
	v_mul_f32_e32 v160, v98, v152
	v_fma_f32 v176, -v209, v160, v176
	v_bfe_u32 v160, v176, 16, 1
	v_add3_u32 v176, v176, v160, s43
	global_store_short_d16_hi v[148:149], v176, off offset:128
	v_mul_f32_e32 v150, v99, v161
	v_fma_f32 v177, -v209, v150, v177
	v_bfe_u32 v150, v177, 16, 1
	v_add3_u32 v177, v177, v150, s43
	global_store_short_d16_hi v[148:149], v177, off offset:2176
	v_mul_f32_e32 v158, v80, v142
	v_fma_f32 v178, -v209, v158, v178
	v_bfe_u32 v158, v178, 16, 1
	v_add3_u32 v178, v178, v158, s43
	global_store_short_d16_hi v[146:147], v178, off offset:192
	v_mul_f32_e32 v159, v81, v145
	v_fma_f32 v179, -v209, v159, v179
	v_bfe_u32 v159, v179, 16, 1
	v_add3_u32 v179, v179, v159, s43
	global_store_short_d16_hi v[146:147], v179, off offset:2240
	v_mul_f32_e32 v160, v82, v152
	v_fma_f32 v180, -v209, v160, v180
	v_bfe_u32 v160, v180, 16, 1
	v_add3_u32 v180, v180, v160, s43
	global_store_short_d16_hi v[148:149], v180, off offset:192
	v_mul_f32_e32 v150, v83, v161
	v_fma_f32 v181, -v209, v150, v181
	v_bfe_u32 v150, v181, 16, 1
	v_add3_u32 v181, v181, v150, s43
	global_store_short_d16_hi v[148:149], v181, off offset:2240
	v_mul_f32_e32 v158, v64, v142
	v_fma_f32 v182, -v209, v158, v182
	v_bfe_u32 v158, v182, 16, 1
	v_add3_u32 v182, v182, v158, s43
	global_store_short_d16_hi v[146:147], v182, off offset:256
	v_mul_f32_e32 v159, v65, v145
	v_fma_f32 v183, -v209, v159, v183
	v_bfe_u32 v159, v183, 16, 1
	v_add3_u32 v183, v183, v159, s43
	global_store_short_d16_hi v[146:147], v183, off offset:2304
	v_mul_f32_e32 v160, v66, v152
	v_fma_f32 v184, -v209, v160, v184
	v_bfe_u32 v160, v184, 16, 1
	v_add3_u32 v184, v184, v160, s43
	global_store_short_d16_hi v[148:149], v184, off offset:256
	v_mul_f32_e32 v150, v67, v161
	v_fma_f32 v185, -v209, v150, v185
	v_bfe_u32 v150, v185, 16, 1
	v_add3_u32 v185, v185, v150, s43
	global_store_short_d16_hi v[148:149], v185, off offset:2304
	v_mul_f32_e32 v158, v48, v142
	v_fma_f32 v186, -v209, v158, v186
	v_bfe_u32 v158, v186, 16, 1
	v_add3_u32 v186, v186, v158, s43
	global_store_short_d16_hi v[146:147], v186, off offset:320
	v_mul_f32_e32 v159, v49, v145
	v_fma_f32 v187, -v209, v159, v187
	v_bfe_u32 v159, v187, 16, 1
	v_add3_u32 v187, v187, v159, s43
	global_store_short_d16_hi v[146:147], v187, off offset:2368
	v_mul_f32_e32 v160, v50, v152
	v_fma_f32 v188, -v209, v160, v188
	v_bfe_u32 v160, v188, 16, 1
	v_add3_u32 v188, v188, v160, s43
	global_store_short_d16_hi v[148:149], v188, off offset:320
	v_mul_f32_e32 v150, v51, v161
	v_fma_f32 v189, -v209, v150, v189
	v_bfe_u32 v150, v189, 16, 1
	v_add3_u32 v189, v189, v150, s43
	global_store_short_d16_hi v[148:149], v189, off offset:2368
	v_mul_f32_e32 v158, v32, v142
	v_fma_f32 v190, -v209, v158, v190
	v_bfe_u32 v158, v190, 16, 1
	v_add3_u32 v190, v190, v158, s43
	global_store_short_d16_hi v[146:147], v190, off offset:384
	v_mul_f32_e32 v159, v33, v145
	v_fma_f32 v191, -v209, v159, v191
	v_bfe_u32 v159, v191, 16, 1
	v_add3_u32 v191, v191, v159, s43
	global_store_short_d16_hi v[146:147], v191, off offset:2432
	v_mul_f32_e32 v160, v34, v152
	v_fma_f32 v192, -v209, v160, v192
	v_bfe_u32 v160, v192, 16, 1
	v_add3_u32 v192, v192, v160, s43
	global_store_short_d16_hi v[148:149], v192, off offset:384
	v_mul_f32_e32 v150, v35, v161
	v_fma_f32 v193, -v209, v150, v193
	v_bfe_u32 v150, v193, 16, 1
	v_add3_u32 v193, v193, v150, s43
	global_store_short_d16_hi v[148:149], v193, off offset:2432
	v_mul_f32_e32 v158, v16, v142
	v_fma_f32 v194, -v209, v158, v194
	v_bfe_u32 v158, v194, 16, 1
	v_add3_u32 v194, v194, v158, s43
	global_store_short_d16_hi v[146:147], v194, off offset:448
	v_mul_f32_e32 v159, v17, v145
	v_fma_f32 v195, -v209, v159, v195
	v_bfe_u32 v159, v195, 16, 1
	v_add3_u32 v195, v195, v159, s43
	global_store_short_d16_hi v[146:147], v195, off offset:2496
	v_mul_f32_e32 v160, v18, v152
	v_fma_f32 v196, -v209, v160, v196
	v_bfe_u32 v160, v196, 16, 1
	v_add3_u32 v196, v196, v160, s43
	global_store_short_d16_hi v[148:149], v196, off offset:448
	v_mul_f32_e32 v150, v19, v161
	v_fma_f32 v197, -v209, v150, v197
	v_bfe_u32 v150, v197, 16, 1
	v_add3_u32 v197, v197, v150, s43
	global_store_short_d16_hi v[148:149], v197, off offset:2496
	global_load_dwordx4 v[166:169], v128, s[96:97]
	s_add_u32 s96, s96, 0x1000
	s_addc_u32 s97, s97, 0
	global_load_dwordx4 v[170:173], v128, s[96:97]
	s_add_u32 s96, s96, 0x1000
	s_addc_u32 s97, s97, 0
	global_load_dwordx4 v[174:177], v128, s[96:97]
	s_add_u32 s96, s96, 0x1000
	s_addc_u32 s97, s97, 0
	global_load_dwordx4 v[178:181], v128, s[96:97]
	s_add_u32 s96, s96, 0x1000
	s_addc_u32 s97, s97, 0
	global_load_dwordx4 v[182:185], v128, s[96:97]
	s_add_u32 s96, s96, 0x1000
	s_addc_u32 s97, s97, 0
	global_load_dwordx4 v[186:189], v128, s[96:97]
	s_add_u32 s96, s96, 0x1000
	s_addc_u32 s97, s97, 0
	global_load_dwordx4 v[190:193], v128, s[96:97]
	s_add_u32 s96, s96, 0x1000
	s_addc_u32 s97, s97, 0
	global_load_dwordx4 v[194:197], v128, s[96:97]
	s_add_u32 s96, s96, 0x1000
	s_addc_u32 s97, s97, 0
	v_lshl_add_u64 v[146:147], v[146:147], 0, s[98:99]
	s_waitcnt vmcnt(40)
	v_lshl_add_u64 v[148:149], v[146:147], 0, s[100:101]
	v_mul_f32_e32 v158, v4, v162
	v_fma_f32 v198, -v209, v158, v198
	v_bfe_u32 v158, v198, 16, 1
	v_add3_u32 v198, v198, v158, s43
	global_store_short_d16_hi v[146:147], v198, off
	v_mul_f32_e32 v159, v5, v163
	v_fma_f32 v199, -v209, v159, v199
	v_bfe_u32 v159, v199, 16, 1
	v_add3_u32 v199, v199, v159, s43
	global_store_short_d16_hi v[146:147], v199, off offset:2048
	v_mul_f32_e32 v160, v6, v164
	v_fma_f32 v200, -v209, v160, v200
	v_bfe_u32 v160, v200, 16, 1
	v_add3_u32 v200, v200, v160, s43
	global_store_short_d16_hi v[148:149], v200, off
	v_mul_f32_e32 v150, v7, v165
	v_fma_f32 v201, -v209, v150, v201
	v_bfe_u32 v150, v201, 16, 1
	v_add3_u32 v201, v201, v150, s43
	global_store_short_d16_hi v[148:149], v201, off offset:2048
	v_mul_f32_e32 v158, v116, v162
	v_fma_f32 v202, -v209, v158, v202
	v_bfe_u32 v158, v202, 16, 1
	v_add3_u32 v202, v202, v158, s43
	global_store_short_d16_hi v[146:147], v202, off offset:64
	v_mul_f32_e32 v159, v117, v163
	v_fma_f32 v203, -v209, v159, v203
	v_bfe_u32 v159, v203, 16, 1
	v_add3_u32 v203, v203, v159, s43
	global_store_short_d16_hi v[146:147], v203, off offset:2112
	v_mul_f32_e32 v160, v118, v164
	v_fma_f32 v204, -v209, v160, v204
	v_bfe_u32 v160, v204, 16, 1
	v_add3_u32 v204, v204, v160, s43
	global_store_short_d16_hi v[148:149], v204, off offset:64
	v_mul_f32_e32 v150, v119, v165
	v_fma_f32 v205, -v209, v150, v205
	v_bfe_u32 v150, v205, 16, 1
	v_add3_u32 v205, v205, v150, s43
	global_store_short_d16_hi v[148:149], v205, off offset:2112
	v_mul_f32_e32 v158, v100, v162
	v_fma_f32 v240, -v209, v158, v240
	v_bfe_u32 v158, v240, 16, 1
	v_add3_u32 v240, v240, v158, s43
	global_store_short_d16_hi v[146:147], v240, off offset:128
	v_mul_f32_e32 v159, v101, v163
	v_fma_f32 v241, -v209, v159, v241
	v_bfe_u32 v159, v241, 16, 1
	v_add3_u32 v241, v241, v159, s43
	global_store_short_d16_hi v[146:147], v241, off offset:2176
	v_mul_f32_e32 v160, v102, v164
	v_fma_f32 v242, -v209, v160, v242
	v_bfe_u32 v160, v242, 16, 1
	v_add3_u32 v242, v242, v160, s43
	global_store_short_d16_hi v[148:149], v242, off offset:128
	v_mul_f32_e32 v150, v103, v165
	v_fma_f32 v243, -v209, v150, v243
	v_bfe_u32 v150, v243, 16, 1
	v_add3_u32 v243, v243, v150, s43
	global_store_short_d16_hi v[148:149], v243, off offset:2176
	v_mul_f32_e32 v158, v84, v162
	v_fma_f32 v244, -v209, v158, v244
	v_bfe_u32 v158, v244, 16, 1
	v_add3_u32 v244, v244, v158, s43
	global_store_short_d16_hi v[146:147], v244, off offset:192
	v_mul_f32_e32 v159, v85, v163
	v_fma_f32 v245, -v209, v159, v245
	v_bfe_u32 v159, v245, 16, 1
	v_add3_u32 v245, v245, v159, s43
	global_store_short_d16_hi v[146:147], v245, off offset:2240
	v_mul_f32_e32 v160, v86, v164
	v_fma_f32 v246, -v209, v160, v246
	v_bfe_u32 v160, v246, 16, 1
	v_add3_u32 v246, v246, v160, s43
	global_store_short_d16_hi v[148:149], v246, off offset:192
	v_mul_f32_e32 v150, v87, v165
	v_fma_f32 v247, -v209, v150, v247
	v_bfe_u32 v150, v247, 16, 1
	v_add3_u32 v247, v247, v150, s43
	global_store_short_d16_hi v[148:149], v247, off offset:2240
	v_mul_f32_e32 v158, v68, v162
	v_fma_f32 v248, -v209, v158, v248
	v_bfe_u32 v158, v248, 16, 1
	v_add3_u32 v248, v248, v158, s43
	global_store_short_d16_hi v[146:147], v248, off offset:256
	v_mul_f32_e32 v159, v69, v163
	v_fma_f32 v249, -v209, v159, v249
	v_bfe_u32 v159, v249, 16, 1
	v_add3_u32 v249, v249, v159, s43
	global_store_short_d16_hi v[146:147], v249, off offset:2304
	v_mul_f32_e32 v160, v70, v164
	v_fma_f32 v250, -v209, v160, v250
	v_bfe_u32 v160, v250, 16, 1
	v_add3_u32 v250, v250, v160, s43
	global_store_short_d16_hi v[148:149], v250, off offset:256
	v_mul_f32_e32 v150, v71, v165
	v_fma_f32 v251, -v209, v150, v251
	v_bfe_u32 v150, v251, 16, 1
	v_add3_u32 v251, v251, v150, s43
	global_store_short_d16_hi v[148:149], v251, off offset:2304
	v_mul_f32_e32 v158, v52, v162
	v_fma_f32 v252, -v209, v158, v252
	v_bfe_u32 v158, v252, 16, 1
	v_add3_u32 v252, v252, v158, s43
	global_store_short_d16_hi v[146:147], v252, off offset:320
	v_mul_f32_e32 v159, v53, v163
	v_fma_f32 v253, -v209, v159, v253
	v_bfe_u32 v159, v253, 16, 1
	v_add3_u32 v253, v253, v159, s43
	global_store_short_d16_hi v[146:147], v253, off offset:2368
	v_mul_f32_e32 v160, v54, v164
	v_fma_f32 v254, -v209, v160, v254
	v_bfe_u32 v160, v254, 16, 1
	v_add3_u32 v254, v254, v160, s43
	global_store_short_d16_hi v[148:149], v254, off offset:320
	v_mul_f32_e32 v150, v55, v165
	v_fma_f32 v255, -v209, v150, v255
	v_bfe_u32 v150, v255, 16, 1
	v_add3_u32 v255, v255, v150, s43
	global_store_short_d16_hi v[148:149], v255, off offset:2368
	v_mul_f32_e32 v158, v36, v162
	v_fma_f32 v232, -v209, v158, v232
	v_bfe_u32 v158, v232, 16, 1
	v_add3_u32 v232, v232, v158, s43
	global_store_short_d16_hi v[146:147], v232, off offset:384
	v_mul_f32_e32 v159, v37, v163
	v_fma_f32 v233, -v209, v159, v233
	v_bfe_u32 v159, v233, 16, 1
	v_add3_u32 v233, v233, v159, s43
	global_store_short_d16_hi v[146:147], v233, off offset:2432
	v_mul_f32_e32 v160, v38, v164
	v_fma_f32 v234, -v209, v160, v234
	v_bfe_u32 v160, v234, 16, 1
	v_add3_u32 v234, v234, v160, s43
	global_store_short_d16_hi v[148:149], v234, off offset:384
	v_mul_f32_e32 v150, v39, v165
	v_fma_f32 v235, -v209, v150, v235
	v_bfe_u32 v150, v235, 16, 1
	v_add3_u32 v235, v235, v150, s43
	global_store_short_d16_hi v[148:149], v235, off offset:2432
	v_mul_f32_e32 v158, v20, v162
	v_fma_f32 v154, -v209, v158, v154
	v_bfe_u32 v158, v154, 16, 1
	v_add3_u32 v154, v154, v158, s43
	global_store_short_d16_hi v[146:147], v154, off offset:448
	v_mul_f32_e32 v159, v21, v163
	v_fma_f32 v155, -v209, v159, v155
	v_bfe_u32 v159, v155, 16, 1
	v_add3_u32 v155, v155, v159, s43
	global_store_short_d16_hi v[146:147], v155, off offset:2496
	v_mul_f32_e32 v160, v22, v164
	v_fma_f32 v156, -v209, v160, v156
	v_bfe_u32 v160, v156, 16, 1
	v_add3_u32 v156, v156, v160, s43
	global_store_short_d16_hi v[148:149], v156, off offset:448
	v_mul_f32_e32 v150, v23, v165
	v_fma_f32 v157, -v209, v150, v157
	v_bfe_u32 v150, v157, 16, 1
	v_add3_u32 v157, v157, v150, s43
	global_store_short_d16_hi v[148:149], v157, off offset:2496
	global_load_dwordx4 v[198:201], v128, s[96:97]
	s_add_u32 s96, s96, 0x1000
	s_addc_u32 s97, s97, 0
	global_load_dwordx4 v[202:205], v128, s[96:97]
	s_add_u32 s96, s96, 0x1000
	s_addc_u32 s97, s97, 0
	global_load_dwordx4 v[240:243], v128, s[96:97]
	s_add_u32 s96, s96, 0x1000
	s_addc_u32 s97, s97, 0
	global_load_dwordx4 v[244:247], v128, s[96:97]
	s_add_u32 s96, s96, 0x1000
	s_addc_u32 s97, s97, 0
	global_load_dwordx4 v[248:251], v128, s[96:97]
	s_add_u32 s96, s96, 0x1000
	s_addc_u32 s97, s97, 0
	global_load_dwordx4 v[252:255], v128, s[96:97]
	s_add_u32 s96, s96, 0x1000
	s_addc_u32 s97, s97, 0
	global_load_dwordx4 v[232:235], v128, s[96:97]
	s_add_u32 s96, s96, 0x1000
	s_addc_u32 s97, s97, 0
	global_load_dwordx4 v[154:157], v128, s[96:97]
	s_add_u32 s96, s96, 0x1000
	s_addc_u32 s97, s97, 0
	v_lshl_add_u64 v[146:147], v[146:147], 0, s[98:99]
	s_waitcnt vmcnt(40)
	v_lshl_add_u64 v[148:149], v[146:147], 0, s[100:101]
	v_mul_f32_e32 v158, v8, v137
	v_fma_f32 v166, -v209, v158, v166
	v_bfe_u32 v158, v166, 16, 1
	v_add3_u32 v166, v166, v158, s43
	global_store_short_d16_hi v[146:147], v166, off
	v_mul_f32_e32 v159, v9, v136
	v_fma_f32 v167, -v209, v159, v167
	v_bfe_u32 v159, v167, 16, 1
	v_add3_u32 v167, v167, v159, s43
	global_store_short_d16_hi v[146:147], v167, off offset:2048
	v_mul_f32_e32 v160, v10, v135
	v_fma_f32 v168, -v209, v160, v168
	v_bfe_u32 v160, v168, 16, 1
	v_add3_u32 v168, v168, v160, s43
	global_store_short_d16_hi v[148:149], v168, off
	v_mul_f32_e32 v150, v11, v134
	v_fma_f32 v169, -v209, v150, v169
	v_bfe_u32 v150, v169, 16, 1
	v_add3_u32 v169, v169, v150, s43
	global_store_short_d16_hi v[148:149], v169, off offset:2048
	v_mul_f32_e32 v158, v120, v137
	v_fma_f32 v170, -v209, v158, v170
	v_bfe_u32 v158, v170, 16, 1
	v_add3_u32 v170, v170, v158, s43
	global_store_short_d16_hi v[146:147], v170, off offset:64
	v_mul_f32_e32 v159, v121, v136
	v_fma_f32 v171, -v209, v159, v171
	v_bfe_u32 v159, v171, 16, 1
	v_add3_u32 v171, v171, v159, s43
	global_store_short_d16_hi v[146:147], v171, off offset:2112
	v_mul_f32_e32 v160, v122, v135
	v_fma_f32 v172, -v209, v160, v172
	v_bfe_u32 v160, v172, 16, 1
	v_add3_u32 v172, v172, v160, s43
	global_store_short_d16_hi v[148:149], v172, off offset:64
	v_mul_f32_e32 v150, v123, v134
	v_fma_f32 v173, -v209, v150, v173
	v_bfe_u32 v150, v173, 16, 1
	v_add3_u32 v173, v173, v150, s43
	global_store_short_d16_hi v[148:149], v173, off offset:2112
	v_mul_f32_e32 v158, v104, v137
	v_fma_f32 v174, -v209, v158, v174
	v_bfe_u32 v158, v174, 16, 1
	v_add3_u32 v174, v174, v158, s43
	global_store_short_d16_hi v[146:147], v174, off offset:128
	v_mul_f32_e32 v159, v105, v136
	v_fma_f32 v175, -v209, v159, v175
	v_bfe_u32 v159, v175, 16, 1
	v_add3_u32 v175, v175, v159, s43
	global_store_short_d16_hi v[146:147], v175, off offset:2176
	v_mul_f32_e32 v160, v106, v135
	v_fma_f32 v176, -v209, v160, v176
	v_bfe_u32 v160, v176, 16, 1
	v_add3_u32 v176, v176, v160, s43
	global_store_short_d16_hi v[148:149], v176, off offset:128
	v_mul_f32_e32 v150, v107, v134
	v_fma_f32 v177, -v209, v150, v177
	v_bfe_u32 v150, v177, 16, 1
	v_add3_u32 v177, v177, v150, s43
	global_store_short_d16_hi v[148:149], v177, off offset:2176
	v_mul_f32_e32 v158, v88, v137
	v_fma_f32 v178, -v209, v158, v178
	v_bfe_u32 v158, v178, 16, 1
	v_add3_u32 v178, v178, v158, s43
	global_store_short_d16_hi v[146:147], v178, off offset:192
	v_mul_f32_e32 v159, v89, v136
	v_fma_f32 v179, -v209, v159, v179
	v_bfe_u32 v159, v179, 16, 1
	v_add3_u32 v179, v179, v159, s43
	global_store_short_d16_hi v[146:147], v179, off offset:2240
	v_mul_f32_e32 v160, v90, v135
	v_fma_f32 v180, -v209, v160, v180
	v_bfe_u32 v160, v180, 16, 1
	v_add3_u32 v180, v180, v160, s43
	global_store_short_d16_hi v[148:149], v180, off offset:192
	v_mul_f32_e32 v150, v91, v134
	v_fma_f32 v181, -v209, v150, v181
	v_bfe_u32 v150, v181, 16, 1
	v_add3_u32 v181, v181, v150, s43
	global_store_short_d16_hi v[148:149], v181, off offset:2240
	v_mul_f32_e32 v158, v72, v137
	v_fma_f32 v182, -v209, v158, v182
	v_bfe_u32 v158, v182, 16, 1
	v_add3_u32 v182, v182, v158, s43
	global_store_short_d16_hi v[146:147], v182, off offset:256
	v_mul_f32_e32 v159, v73, v136
	v_fma_f32 v183, -v209, v159, v183
	v_bfe_u32 v159, v183, 16, 1
	v_add3_u32 v183, v183, v159, s43
	global_store_short_d16_hi v[146:147], v183, off offset:2304
	v_mul_f32_e32 v160, v74, v135
	v_fma_f32 v184, -v209, v160, v184
	v_bfe_u32 v160, v184, 16, 1
	v_add3_u32 v184, v184, v160, s43
	global_store_short_d16_hi v[148:149], v184, off offset:256
	v_mul_f32_e32 v150, v75, v134
	v_fma_f32 v185, -v209, v150, v185
	v_bfe_u32 v150, v185, 16, 1
	v_add3_u32 v185, v185, v150, s43
	global_store_short_d16_hi v[148:149], v185, off offset:2304
	v_mul_f32_e32 v158, v56, v137
	v_fma_f32 v186, -v209, v158, v186
	v_bfe_u32 v158, v186, 16, 1
	v_add3_u32 v186, v186, v158, s43
	global_store_short_d16_hi v[146:147], v186, off offset:320
	v_mul_f32_e32 v159, v57, v136
	v_fma_f32 v187, -v209, v159, v187
	v_bfe_u32 v159, v187, 16, 1
	v_add3_u32 v187, v187, v159, s43
	global_store_short_d16_hi v[146:147], v187, off offset:2368
	v_mul_f32_e32 v160, v58, v135
	v_fma_f32 v188, -v209, v160, v188
	v_bfe_u32 v160, v188, 16, 1
	v_add3_u32 v188, v188, v160, s43
	global_store_short_d16_hi v[148:149], v188, off offset:320
	v_mul_f32_e32 v150, v59, v134
	v_fma_f32 v189, -v209, v150, v189
	v_bfe_u32 v150, v189, 16, 1
	v_add3_u32 v189, v189, v150, s43
	global_store_short_d16_hi v[148:149], v189, off offset:2368
	v_mul_f32_e32 v158, v40, v137
	v_fma_f32 v190, -v209, v158, v190
	v_bfe_u32 v158, v190, 16, 1
	v_add3_u32 v190, v190, v158, s43
	global_store_short_d16_hi v[146:147], v190, off offset:384
	v_mul_f32_e32 v159, v41, v136
	v_fma_f32 v191, -v209, v159, v191
	v_bfe_u32 v159, v191, 16, 1
	v_add3_u32 v191, v191, v159, s43
	global_store_short_d16_hi v[146:147], v191, off offset:2432
	v_mul_f32_e32 v160, v42, v135
	v_fma_f32 v192, -v209, v160, v192
	v_bfe_u32 v160, v192, 16, 1
	v_add3_u32 v192, v192, v160, s43
	global_store_short_d16_hi v[148:149], v192, off offset:384
	v_mul_f32_e32 v150, v43, v134
	v_fma_f32 v193, -v209, v150, v193
	v_bfe_u32 v150, v193, 16, 1
	v_add3_u32 v193, v193, v150, s43
	global_store_short_d16_hi v[148:149], v193, off offset:2432
	v_mul_f32_e32 v158, v24, v137
	v_fma_f32 v194, -v209, v158, v194
	v_bfe_u32 v158, v194, 16, 1
	v_add3_u32 v194, v194, v158, s43
	global_store_short_d16_hi v[146:147], v194, off offset:448
	v_mul_f32_e32 v159, v25, v136
	v_fma_f32 v195, -v209, v159, v195
	v_bfe_u32 v159, v195, 16, 1
	v_add3_u32 v195, v195, v159, s43
	global_store_short_d16_hi v[146:147], v195, off offset:2496
	v_mul_f32_e32 v160, v26, v135
	v_fma_f32 v196, -v209, v160, v196
	v_bfe_u32 v160, v196, 16, 1
	v_add3_u32 v196, v196, v160, s43
	global_store_short_d16_hi v[148:149], v196, off offset:448
	v_mul_f32_e32 v150, v27, v134
	v_fma_f32 v197, -v209, v150, v197
	v_bfe_u32 v150, v197, 16, 1
	v_add3_u32 v197, v197, v150, s43
	global_store_short_d16_hi v[148:149], v197, off offset:2496
	v_lshl_add_u64 v[146:147], v[146:147], 0, s[98:99]
	s_waitcnt vmcnt(32)
	v_lshl_add_u64 v[148:149], v[146:147], 0, s[100:101]
	v_mul_f32_e32 v158, v12, v133
	v_fma_f32 v198, -v209, v158, v198
	v_bfe_u32 v158, v198, 16, 1
	v_add3_u32 v198, v198, v158, s43
	global_store_short_d16_hi v[146:147], v198, off
	v_mul_f32_e32 v159, v13, v132
	v_fma_f32 v199, -v209, v159, v199
	v_bfe_u32 v159, v199, 16, 1
	v_add3_u32 v199, v199, v159, s43
	global_store_short_d16_hi v[146:147], v199, off offset:2048
	v_mul_f32_e32 v160, v14, v131
	v_fma_f32 v200, -v209, v160, v200
	v_bfe_u32 v160, v200, 16, 1
	v_add3_u32 v200, v200, v160, s43
	global_store_short_d16_hi v[148:149], v200, off
	v_mul_f32_e32 v150, v15, v130
	v_fma_f32 v201, -v209, v150, v201
	v_bfe_u32 v150, v201, 16, 1
	v_add3_u32 v201, v201, v150, s43
	global_store_short_d16_hi v[148:149], v201, off offset:2048
	v_mul_f32_e32 v158, v124, v133
	v_fma_f32 v202, -v209, v158, v202
	v_bfe_u32 v158, v202, 16, 1
	v_add3_u32 v202, v202, v158, s43
	global_store_short_d16_hi v[146:147], v202, off offset:64
	v_mul_f32_e32 v159, v125, v132
	v_fma_f32 v203, -v209, v159, v203
	v_bfe_u32 v159, v203, 16, 1
	v_add3_u32 v203, v203, v159, s43
	global_store_short_d16_hi v[146:147], v203, off offset:2112
	v_mul_f32_e32 v160, v126, v131
	v_fma_f32 v204, -v209, v160, v204
	v_bfe_u32 v160, v204, 16, 1
	v_add3_u32 v204, v204, v160, s43
	global_store_short_d16_hi v[148:149], v204, off offset:64
	v_mul_f32_e32 v150, v127, v130
	v_fma_f32 v205, -v209, v150, v205
	v_bfe_u32 v150, v205, 16, 1
	v_add3_u32 v205, v205, v150, s43
	global_store_short_d16_hi v[148:149], v205, off offset:2112
	v_mul_f32_e32 v158, v108, v133
	v_fma_f32 v240, -v209, v158, v240
	v_bfe_u32 v158, v240, 16, 1
	v_add3_u32 v240, v240, v158, s43
	global_store_short_d16_hi v[146:147], v240, off offset:128
	v_mul_f32_e32 v159, v109, v132
	v_fma_f32 v241, -v209, v159, v241
	v_bfe_u32 v159, v241, 16, 1
	v_add3_u32 v241, v241, v159, s43
	global_store_short_d16_hi v[146:147], v241, off offset:2176
	v_mul_f32_e32 v160, v110, v131
	v_fma_f32 v242, -v209, v160, v242
	v_bfe_u32 v160, v242, 16, 1
	v_add3_u32 v242, v242, v160, s43
	global_store_short_d16_hi v[148:149], v242, off offset:128
	v_mul_f32_e32 v150, v111, v130
	v_fma_f32 v243, -v209, v150, v243
	v_bfe_u32 v150, v243, 16, 1
	v_add3_u32 v243, v243, v150, s43
	global_store_short_d16_hi v[148:149], v243, off offset:2176
	v_mul_f32_e32 v158, v92, v133
	v_fma_f32 v244, -v209, v158, v244
	v_bfe_u32 v158, v244, 16, 1
	v_add3_u32 v244, v244, v158, s43
	global_store_short_d16_hi v[146:147], v244, off offset:192
	v_mul_f32_e32 v159, v93, v132
	v_fma_f32 v245, -v209, v159, v245
	v_bfe_u32 v159, v245, 16, 1
	v_add3_u32 v245, v245, v159, s43
	global_store_short_d16_hi v[146:147], v245, off offset:2240
	v_mul_f32_e32 v160, v94, v131
	v_fma_f32 v246, -v209, v160, v246
	v_bfe_u32 v160, v246, 16, 1
	v_add3_u32 v246, v246, v160, s43
	global_store_short_d16_hi v[148:149], v246, off offset:192
	v_mul_f32_e32 v150, v95, v130
	v_fma_f32 v247, -v209, v150, v247
	v_bfe_u32 v150, v247, 16, 1
	v_add3_u32 v247, v247, v150, s43
	global_store_short_d16_hi v[148:149], v247, off offset:2240
	v_mul_f32_e32 v158, v76, v133
	v_fma_f32 v248, -v209, v158, v248
	v_bfe_u32 v158, v248, 16, 1
	v_add3_u32 v248, v248, v158, s43
	global_store_short_d16_hi v[146:147], v248, off offset:256
	v_mul_f32_e32 v159, v77, v132
	v_fma_f32 v249, -v209, v159, v249
	v_bfe_u32 v159, v249, 16, 1
	v_add3_u32 v249, v249, v159, s43
	global_store_short_d16_hi v[146:147], v249, off offset:2304
	v_mul_f32_e32 v160, v78, v131
	v_fma_f32 v250, -v209, v160, v250
	v_bfe_u32 v160, v250, 16, 1
	v_add3_u32 v250, v250, v160, s43
	global_store_short_d16_hi v[148:149], v250, off offset:256
	v_mul_f32_e32 v150, v79, v130
	v_fma_f32 v251, -v209, v150, v251
	v_bfe_u32 v150, v251, 16, 1
	v_add3_u32 v251, v251, v150, s43
	global_store_short_d16_hi v[148:149], v251, off offset:2304
	v_mul_f32_e32 v158, v60, v133
	v_fma_f32 v252, -v209, v158, v252
	v_bfe_u32 v158, v252, 16, 1
	v_add3_u32 v252, v252, v158, s43
	global_store_short_d16_hi v[146:147], v252, off offset:320
	v_mul_f32_e32 v159, v61, v132
	v_fma_f32 v253, -v209, v159, v253
	v_bfe_u32 v159, v253, 16, 1
	v_add3_u32 v253, v253, v159, s43
	global_store_short_d16_hi v[146:147], v253, off offset:2368
	v_mul_f32_e32 v160, v62, v131
	v_fma_f32 v254, -v209, v160, v254
	v_bfe_u32 v160, v254, 16, 1
	v_add3_u32 v254, v254, v160, s43
	global_store_short_d16_hi v[148:149], v254, off offset:320
	v_mul_f32_e32 v150, v63, v130
	v_fma_f32 v255, -v209, v150, v255
	v_bfe_u32 v150, v255, 16, 1
	v_add3_u32 v255, v255, v150, s43
	global_store_short_d16_hi v[148:149], v255, off offset:2368
	v_mul_f32_e32 v158, v44, v133
	v_fma_f32 v232, -v209, v158, v232
	v_bfe_u32 v158, v232, 16, 1
	v_add3_u32 v232, v232, v158, s43
	global_store_short_d16_hi v[146:147], v232, off offset:384
	v_mul_f32_e32 v159, v45, v132
	v_fma_f32 v233, -v209, v159, v233
	v_bfe_u32 v159, v233, 16, 1
	v_add3_u32 v233, v233, v159, s43
	global_store_short_d16_hi v[146:147], v233, off offset:2432
	v_mul_f32_e32 v160, v46, v131
	v_fma_f32 v234, -v209, v160, v234
	v_bfe_u32 v160, v234, 16, 1
	v_add3_u32 v234, v234, v160, s43
	global_store_short_d16_hi v[148:149], v234, off offset:384
	v_mul_f32_e32 v150, v47, v130
	v_fma_f32 v235, -v209, v150, v235
	v_bfe_u32 v150, v235, 16, 1
	v_add3_u32 v235, v235, v150, s43
	global_store_short_d16_hi v[148:149], v235, off offset:2432
	v_mul_f32_e32 v158, v28, v133
	v_fma_f32 v154, -v209, v158, v154
	v_bfe_u32 v158, v154, 16, 1
	v_add3_u32 v154, v154, v158, s43
	global_store_short_d16_hi v[146:147], v154, off offset:448
	v_mul_f32_e32 v159, v29, v132
	v_fma_f32 v155, -v209, v159, v155
	v_bfe_u32 v159, v155, 16, 1
	v_add3_u32 v155, v155, v159, s43
	global_store_short_d16_hi v[146:147], v155, off offset:2496
	v_mul_f32_e32 v160, v30, v131
	v_fma_f32 v156, -v209, v160, v156
	v_bfe_u32 v160, v156, 16, 1
	v_add3_u32 v156, v156, v160, s43
	global_store_short_d16_hi v[148:149], v156, off offset:448
	v_mul_f32_e32 v150, v31, v130
	v_fma_f32 v157, -v209, v150, v157
	v_bfe_u32 v150, v157, 16, 1
	v_add3_u32 v157, v157, v150, s43
	global_store_short_d16_hi v[148:149], v157, off offset:2496
	s_branch .LBB0_901
